# v95 with the two-pass-A waves at 2 rows (1152 waves x 11 + 64 x 10): s2 split re-tuned after the V-transpose speed-up
# speedup vs baseline: 1.0006x; 1.0006x over previous
.LBB0_501:
	s_andn2_saveexec_b64 s[2:3], s[16:17]
	s_cbranch_execz .LBB0_530
	v_add_u32_e32 v4, 0xffffff00, v81
	s_mov_b32 s0, 0xe38f
	v_mul_u32_u24_sdwa v1, v4, s0 dst_sel:DWORD dst_unused:UNUSED_PAD src0_sel:WORD_0 src1_sel:DWORD
	v_lshrrev_b32_e32 v2, 21, v1
	v_mul_lo_u16_e32 v3, 36, v2
	v_sub_u16_e32 v3, v4, v3
	v_mov_b32_e32 v0, v236
	v_lshrrev_b32_e32 v5, 22, v1
	v_cmp_lt_u16_e32 vcc, 31, v3
	v_lshlrev_b16_e32 v3, 6, v3
	s_and_saveexec_b64 s[0:1], vcc
	s_xor_b64 s[0:1], exec, s[0:1]
	v_lshlrev_b32_e32 v1, 8, v5
	s_movk_i32 s4, 0x3800
	v_add3_u32 v1, v3, v1, s4
	s_andn2_saveexec_b64 s[0:1], s[0:1]
	v_lshl_or_b32 v1, v5, 11, v3
	s_or_b64 exec, exec, s[0:1]
	v_readlane_b32 s8, v254, 28
	v_readlane_b32 s9, v254, 29
	s_movk_i32 s6, 0x1200
	v_lshlrev_b32_e32 v8, 7, v2
	v_mov_b64_e32 v[6:7], s[8:9]
	v_and_b32_e32 v5, 63, v0
	v_mad_u64_u32 v[0:1], s[0:1], v1, s6, v[6:7]
	v_and_b32_e32 v160, 0x80, v8
	v_lshl_add_u64 v[0:1], v[0:1], 0, v[160:161]
	v_lshlrev_b32_e32 v160, 1, v5
	v_lshl_add_u64 v[0:1], v[0:1], 0, v[160:161]
	s_mov_b32 s0, 0xb200000
	v_add_co_u32_e32 v8, vcc, s0, v0
	s_mov_b32 s0, 0xb201000
	s_nop 0
	v_addc_co_u32_e32 v9, vcc, 0, v1, vcc
	v_add_co_u32_e32 v10, vcc, s0, v0
	s_mov_b32 s0, 0xb202000
	s_nop 0
	v_addc_co_u32_e32 v11, vcc, 0, v1, vcc
	v_add_co_u32_e32 v12, vcc, s0, v0
	s_mov_b32 s0, 0xb203000
	s_nop 0
	v_addc_co_u32_e32 v13, vcc, 0, v1, vcc
	v_add_co_u32_e32 v14, vcc, s0, v0
	s_mov_b32 s0, 0xb204000
	s_nop 0
	v_addc_co_u32_e32 v15, vcc, 0, v1, vcc
	v_add_co_u32_e32 v16, vcc, s0, v0
	s_mov_b32 s0, 0xb206000
	s_nop 0
	v_addc_co_u32_e32 v17, vcc, 0, v1, vcc
	v_add_co_u32_e32 v18, vcc, s0, v0
	s_mov_b32 s0, 0xb207000
	s_nop 0
	v_addc_co_u32_e32 v19, vcc, 0, v1, vcc
	v_add_co_u32_e32 v20, vcc, s0, v0
	s_mov_b32 s0, 0xb208000
	s_nop 0
	v_addc_co_u32_e32 v21, vcc, 0, v1, vcc
	v_add_co_u32_e32 v22, vcc, s0, v0
	v_lshl_or_b32 v2, v2, 6, v5
	s_nop 0
	v_addc_co_u32_e32 v23, vcc, 0, v1, vcc
	global_load_ushort v8, v[8:9], off offset:1792
	s_nop 0
	global_load_ushort v9, v[10:11], off offset:2304
	global_load_ushort v24, v[12:13], off offset:2816
	global_load_ushort v25, v[14:15], off offset:3328
	global_load_ushort v26, v[16:17], off offset:3840
	global_load_ushort v27, v[18:19], off offset:256
	global_load_ushort v28, v[20:21], off offset:768
	global_load_ushort v29, v[22:23], off offset:1280
	s_mov_b32 s98, 0xb209700
	s_mov_b32 s99, 0
	v_lshl_add_u64 v[250:251], v[0:1], 0, s[98:99]
	s_movk_i32 s98, 0x1200
	s_nop 0
	global_load_ushort v196, v[250:251], off
	v_lshl_add_u64 v[250:251], v[250:251], 0, s[98:99]
	s_nop 0
	global_load_ushort v197, v[250:251], off
	v_lshl_add_u64 v[250:251], v[250:251], 0, s[98:99]
	s_nop 0
	global_load_ushort v198, v[250:251], off
	v_lshl_add_u64 v[250:251], v[250:251], 0, s[98:99]
	s_nop 0
	global_load_ushort v199, v[250:251], off
	v_lshl_add_u64 v[250:251], v[250:251], 0, s[98:99]
	s_nop 0
	global_load_ushort v200, v[250:251], off
	v_lshl_add_u64 v[250:251], v[250:251], 0, s[98:99]
	s_nop 0
	global_load_ushort v201, v[250:251], off
	v_lshl_add_u64 v[250:251], v[250:251], 0, s[98:99]
	s_nop 0
	global_load_ushort v202, v[250:251], off
	v_lshl_add_u64 v[250:251], v[250:251], 0, s[98:99]
	s_nop 0
	global_load_ushort v203, v[250:251], off
	v_lshl_add_u64 v[250:251], v[250:251], 0, s[98:99]
	s_nop 0
	global_load_ushort v206, v[250:251], off
	v_lshl_add_u64 v[250:251], v[250:251], 0, s[98:99]
	s_nop 0
	global_load_ushort v207, v[250:251], off
	v_lshl_add_u64 v[250:251], v[250:251], 0, s[98:99]
	s_nop 0
	global_load_ushort v208, v[250:251], off
	v_lshl_add_u64 v[250:251], v[250:251], 0, s[98:99]
	s_nop 0
	global_load_ushort v209, v[250:251], off
	v_lshl_add_u64 v[250:251], v[250:251], 0, s[98:99]
	s_nop 0
	global_load_ushort v210, v[250:251], off
	v_lshl_add_u64 v[250:251], v[250:251], 0, s[98:99]
	s_nop 0
	global_load_ushort v211, v[250:251], off
	v_lshl_add_u64 v[250:251], v[250:251], 0, s[98:99]
	s_nop 0
	global_load_ushort v212, v[250:251], off
	v_lshl_add_u64 v[250:251], v[250:251], 0, s[98:99]
	s_nop 0
	global_load_ushort v213, v[250:251], off
	v_lshl_add_u64 v[250:251], v[250:251], 0, s[98:99]
	s_nop 0
	global_load_ushort v214, v[250:251], off
	v_lshl_add_u64 v[250:251], v[250:251], 0, s[98:99]
	s_nop 0
	global_load_ushort v215, v[250:251], off
	v_lshl_add_u64 v[250:251], v[250:251], 0, s[98:99]
	s_nop 0
	global_load_ushort v216, v[250:251], off
	v_lshl_add_u64 v[250:251], v[250:251], 0, s[98:99]
	s_nop 0
	global_load_ushort v217, v[250:251], off
	v_lshl_add_u64 v[250:251], v[250:251], 0, s[98:99]
	s_nop 0
	global_load_ushort v218, v[250:251], off
	v_lshl_add_u64 v[250:251], v[250:251], 0, s[98:99]
	s_nop 0
	global_load_ushort v219, v[250:251], off
	v_lshl_add_u64 v[250:251], v[250:251], 0, s[98:99]
	s_nop 0
	global_load_ushort v220, v[250:251], off
	v_lshl_add_u64 v[250:251], v[250:251], 0, s[98:99]
	s_nop 0
	global_load_ushort v221, v[250:251], off
	v_lshl_add_u64 v[250:251], v[250:251], 0, s[98:99]
	s_nop 0
	global_load_ushort v222, v[250:251], off
	v_lshl_add_u64 v[250:251], v[250:251], 0, s[98:99]
	s_nop 0
	global_load_ushort v223, v[250:251], off
	v_lshl_add_u64 v[250:251], v[250:251], 0, s[98:99]
	s_nop 0
	global_load_ushort v224, v[250:251], off
	v_lshl_add_u64 v[250:251], v[250:251], 0, s[98:99]
	s_nop 0
	global_load_ushort v225, v[250:251], off
	v_lshl_add_u64 v[250:251], v[250:251], 0, s[98:99]
	s_nop 0
	global_load_ushort v226, v[250:251], off
	v_lshl_add_u64 v[250:251], v[250:251], 0, s[98:99]
	s_nop 0
	global_load_ushort v227, v[250:251], off
	v_lshl_add_u64 v[250:251], v[250:251], 0, s[98:99]
	s_nop 0
	global_load_ushort v228, v[250:251], off
	v_lshl_add_u64 v[250:251], v[250:251], 0, s[98:99]
	s_nop 0
	global_load_ushort v229, v[250:251], off
	v_lshl_add_u64 v[250:251], v[250:251], 0, s[98:99]
	s_nop 0
	global_load_ushort v230, v[250:251], off
	v_lshl_add_u64 v[250:251], v[250:251], 0, s[98:99]
	s_nop 0
	global_load_ushort v231, v[250:251], off
	v_lshl_add_u64 v[250:251], v[250:251], 0, s[98:99]
	s_nop 0
	global_load_ushort v232, v[250:251], off
	v_lshl_add_u64 v[250:251], v[250:251], 0, s[98:99]
	s_nop 0
	global_load_ushort v233, v[250:251], off
	v_lshl_add_u64 v[250:251], v[250:251], 0, s[98:99]
	s_nop 0
	global_load_ushort v234, v[250:251], off
	v_lshl_add_u64 v[250:251], v[250:251], 0, s[98:99]
	s_nop 0
	global_load_ushort v235, v[250:251], off
	v_lshl_add_u64 v[250:251], v[250:251], 0, s[98:99]
	s_nop 0
	global_load_ushort v240, v[250:251], off
	v_lshl_add_u64 v[250:251], v[250:251], 0, s[98:99]
	s_nop 0
	global_load_ushort v241, v[250:251], off
	v_lshl_add_u64 v[250:251], v[250:251], 0, s[98:99]
	s_nop 0
	global_load_ushort v242, v[250:251], off
	v_lshl_add_u64 v[250:251], v[250:251], 0, s[98:99]
	s_nop 0
	global_load_ushort v243, v[250:251], off
	v_lshl_add_u64 v[250:251], v[250:251], 0, s[98:99]
	s_nop 0
	global_load_ushort v248, v[250:251], off
	v_lshl_add_u64 v[250:251], v[250:251], 0, s[98:99]
	s_nop 0
	global_load_ushort v249, v[250:251], off
	v_lshl_add_u64 v[250:251], v[250:251], 0, s[98:99]
	v_mad_u64_u32 v[6:7], s[0:1], v2, s6, v[6:7]
	s_mov_b32 s0, 0xb209000
	s_nop 0
	v_add_co_u32_e32 v10, vcc, s0, v0
	s_mov_b32 s0, 0xb20a000
	s_nop 0
	v_addc_co_u32_e32 v11, vcc, 0, v1, vcc
	v_add_co_u32_e32 v12, vcc, s0, v0
	s_mov_b32 s0, 0xb20b000
	s_nop 0
	v_addc_co_u32_e32 v13, vcc, 0, v1, vcc
	v_add_co_u32_e32 v14, vcc, s0, v0
	s_mov_b32 s0, 0xb20c000
	s_nop 0
	v_addc_co_u32_e32 v15, vcc, 0, v1, vcc
	v_add_co_u32_e32 v16, vcc, s0, v0
	s_mov_b32 s0, 0xb20d000
	s_nop 0
	v_addc_co_u32_e32 v17, vcc, 0, v1, vcc
	v_add_co_u32_e32 v18, vcc, s0, v0
	s_mov_b32 s0, 0xb20f000
	s_nop 0
	v_addc_co_u32_e32 v19, vcc, 0, v1, vcc
	v_lshlrev_b32_e32 v160, 1, v3
	v_add_co_u32_e32 v20, vcc, s0, v0
	v_lshl_add_u64 v[2:3], v[6:7], 0, v[160:161]
	s_nop 0
	v_addc_co_u32_e32 v21, vcc, 0, v1, vcc
	s_mov_b32 s0, 0x19300000
	v_add_co_u32_e32 v22, vcc, s0, v2
	s_mov_b32 s0, 0xb210000
	s_nop 0
	v_addc_co_u32_e32 v23, vcc, 0, v3, vcc
	v_readlane_b32 s10, v255, 11
	v_readlane_b32 s11, v255, 12
	v_mov_b32_e32 v60, 0
	s_mov_b32 s14, 0
	v_mov_b32_e32 v38, 0
	v_mov_b32_e32 v39, v60
	v_mov_b32_e32 v36, 0
	v_mov_b32_e32 v37, v60
	s_waitcnt vmcnt(0)
	v_lshl_or_b32 v6, v9, 16, v8
	v_lshl_or_b32 v7, v25, 16, v24
	v_lshl_or_b32 v8, v27, 16, v26
	v_lshl_or_b32 v9, v29, 16, v28
	global_store_dwordx4 v[22:23], v[6:9], off
	s_nop 1
	v_add_co_u32_e32 v6, vcc, s0, v0
	s_mov_b32 s0, 0xb211000
	s_nop 0
	v_addc_co_u32_e32 v7, vcc, 0, v1, vcc
	v_add_co_u32_e32 v8, vcc, s0, v0
	s_mov_b32 s0, 0xb212000
	s_nop 0
	v_addc_co_u32_e32 v9, vcc, 0, v1, vcc
	global_load_ushort v5, v[10:11], off offset:1792
	global_load_ushort v26, v[12:13], off offset:2304
	global_load_ushort v27, v[14:15], off offset:2816
	global_load_ushort v28, v[16:17], off offset:3328
	global_load_ushort v29, v[18:19], off offset:3840
	global_load_ushort v30, v[20:21], off offset:256
	global_load_ushort v31, v[6:7], off offset:768
	s_nop 0
	global_load_ushort v9, v[8:9], off offset:1280
	v_add_co_u32_e32 v10, vcc, s0, v0
	s_mov_b32 s0, 0xb213000
	s_nop 0
	v_addc_co_u32_e32 v11, vcc, 0, v1, vcc
	v_add_co_u32_e32 v12, vcc, s0, v0
	s_mov_b32 s0, 0xb214000
	s_nop 0
	v_addc_co_u32_e32 v13, vcc, 0, v1, vcc
	v_add_co_u32_e32 v14, vcc, s0, v0
	s_mov_b32 s0, 0xb215000
	s_nop 0
	v_addc_co_u32_e32 v15, vcc, 0, v1, vcc
	v_add_co_u32_e32 v16, vcc, s0, v0
	s_mov_b32 s0, 0xb216000
	s_nop 0
	v_addc_co_u32_e32 v17, vcc, 0, v1, vcc
	v_add_co_u32_e32 v18, vcc, s0, v0
	s_mov_b32 s0, 0xb218000
	s_nop 0
	v_addc_co_u32_e32 v19, vcc, 0, v1, vcc
	v_add_co_u32_e32 v20, vcc, s0, v0
	s_mov_b32 s0, 0xb219000
	s_nop 0
	v_addc_co_u32_e32 v21, vcc, 0, v1, vcc
	v_add_co_u32_e32 v22, vcc, s0, v0
	s_mov_b32 s0, 0xb21a000
	s_nop 0
	v_addc_co_u32_e32 v23, vcc, 0, v1, vcc
	v_add_co_u32_e32 v24, vcc, s0, v0
	s_mov_b64 s[0:1], 0x19300000
	v_lshl_add_u64 v[2:3], v[2:3], 0, s[0:1]
	v_addc_co_u32_e32 v25, vcc, 0, v1, vcc
	s_mov_b32 s0, 0xb21b000
	s_waitcnt vmcnt(0)
	v_lshl_or_b32 v6, v26, 16, v5
	v_lshl_or_b32 v7, v28, 16, v27
	v_lshl_or_b32 v8, v30, 16, v29
	v_lshl_or_b32 v9, v9, 16, v31
	global_store_dwordx4 v[2:3], v[6:9], off offset:16
	global_load_ushort v5, v[10:11], off offset:1792
	s_nop 0
	global_load_ushort v6, v[12:13], off offset:2304
	global_load_ushort v7, v[14:15], off offset:2816
	global_load_ushort v8, v[16:17], off offset:3328
	global_load_ushort v9, v[18:19], off offset:3840
	global_load_ushort v26, v[20:21], off offset:256
	global_load_ushort v27, v[22:23], off offset:768
	global_load_ushort v28, v[24:25], off offset:1280
	v_add_co_u32_e32 v10, vcc, s0, v0
	s_mov_b32 s0, 0xb21c000
	s_nop 0
	v_addc_co_u32_e32 v11, vcc, 0, v1, vcc
	v_add_co_u32_e32 v12, vcc, s0, v0
	s_mov_b32 s0, 0xb21d000
	s_nop 0
	v_addc_co_u32_e32 v13, vcc, 0, v1, vcc
	v_add_co_u32_e32 v14, vcc, s0, v0
	s_mov_b32 s0, 0xb21e000
	s_nop 0
	v_addc_co_u32_e32 v15, vcc, 0, v1, vcc
	v_add_co_u32_e32 v16, vcc, s0, v0
	s_mov_b32 s0, 0xb21f000
	s_nop 0
	v_addc_co_u32_e32 v17, vcc, 0, v1, vcc
	v_add_co_u32_e32 v18, vcc, s0, v0
	s_mov_b32 s0, 0xb221000
	s_nop 0
	v_addc_co_u32_e32 v19, vcc, 0, v1, vcc
	v_add_co_u32_e32 v20, vcc, s0, v0
	s_mov_b32 s0, 0xb222000
	s_nop 0
	v_addc_co_u32_e32 v21, vcc, 0, v1, vcc
	v_add_co_u32_e32 v22, vcc, s0, v0
	s_mov_b32 s0, 0xb223000
	s_nop 0
	v_addc_co_u32_e32 v23, vcc, 0, v1, vcc
	v_add_co_u32_e32 v24, vcc, s0, v0
	s_mov_b32 s0, 0xb224000
	s_nop 0
	v_addc_co_u32_e32 v25, vcc, 0, v1, vcc
	s_waitcnt vmcnt(0)
	v_lshl_or_b32 v6, v6, 16, v5
	v_lshl_or_b32 v7, v8, 16, v7
	v_lshl_or_b32 v8, v26, 16, v9
	v_lshl_or_b32 v9, v28, 16, v27
	global_store_dwordx4 v[2:3], v[6:9], off offset:32
	global_load_ushort v5, v[10:11], off offset:1792
	s_nop 0
	global_load_ushort v6, v[12:13], off offset:2304
	global_load_ushort v7, v[14:15], off offset:2816
	global_load_ushort v8, v[16:17], off offset:3328
	global_load_ushort v9, v[18:19], off offset:3840
	global_load_ushort v26, v[20:21], off offset:256
	global_load_ushort v27, v[22:23], off offset:768
	global_load_ushort v28, v[24:25], off offset:1280
	v_add_co_u32_e32 v10, vcc, s0, v0
	s_mov_b32 s0, 0xb225000
	s_nop 0
	v_addc_co_u32_e32 v11, vcc, 0, v1, vcc
	v_add_co_u32_e32 v12, vcc, s0, v0
	s_mov_b32 s0, 0xb226000
	s_nop 0
	v_addc_co_u32_e32 v13, vcc, 0, v1, vcc
	v_add_co_u32_e32 v14, vcc, s0, v0
	s_mov_b32 s0, 0xb227000
	s_nop 0
	v_addc_co_u32_e32 v15, vcc, 0, v1, vcc
	v_add_co_u32_e32 v16, vcc, s0, v0
	s_mov_b32 s0, 0xb228000
	s_nop 0
	v_addc_co_u32_e32 v17, vcc, 0, v1, vcc
	v_add_co_u32_e32 v18, vcc, s0, v0
	s_mov_b32 s0, 0xb22a000
	s_nop 0
	v_addc_co_u32_e32 v19, vcc, 0, v1, vcc
	v_add_co_u32_e32 v20, vcc, s0, v0
	s_mov_b32 s0, 0xb22b000
	s_nop 0
	v_addc_co_u32_e32 v21, vcc, 0, v1, vcc
	v_add_co_u32_e32 v22, vcc, s0, v0
	s_mov_b32 s0, 0xb22c000
	s_nop 0
	v_addc_co_u32_e32 v23, vcc, 0, v1, vcc
	v_add_co_u32_e32 v24, vcc, s0, v0
	s_mov_b32 s0, 0xb22d000
	s_nop 0
	v_addc_co_u32_e32 v25, vcc, 0, v1, vcc
	s_waitcnt vmcnt(0)
	v_lshl_or_b32 v6, v6, 16, v5
	v_lshl_or_b32 v7, v8, 16, v7
	v_lshl_or_b32 v8, v26, 16, v9
	v_lshl_or_b32 v9, v28, 16, v27
	global_store_dwordx4 v[2:3], v[6:9], off offset:48
	global_load_ushort v5, v[10:11], off offset:1792
	s_nop 0
	global_load_ushort v6, v[12:13], off offset:2304
	global_load_ushort v7, v[14:15], off offset:2816
	global_load_ushort v8, v[16:17], off offset:3328
	global_load_ushort v9, v[18:19], off offset:3840
	global_load_ushort v26, v[20:21], off offset:256
	global_load_ushort v27, v[22:23], off offset:768
	global_load_ushort v28, v[24:25], off offset:1280
	v_add_co_u32_e32 v10, vcc, s0, v0
	s_mov_b32 s0, 0xb22e000
	s_nop 0
	v_addc_co_u32_e32 v11, vcc, 0, v1, vcc
	v_add_co_u32_e32 v12, vcc, s0, v0
	s_mov_b32 s0, 0xb22f000
	s_nop 0
	v_addc_co_u32_e32 v13, vcc, 0, v1, vcc
	v_add_co_u32_e32 v14, vcc, s0, v0
	s_mov_b32 s0, 0xb230000
	s_nop 0
	v_addc_co_u32_e32 v15, vcc, 0, v1, vcc
	v_add_co_u32_e32 v16, vcc, s0, v0
	s_mov_b32 s0, 0xb231000
	s_nop 0
	v_addc_co_u32_e32 v17, vcc, 0, v1, vcc
	v_add_co_u32_e32 v18, vcc, s0, v0
	s_mov_b32 s0, 0xb233000
	s_nop 0
	v_addc_co_u32_e32 v19, vcc, 0, v1, vcc
	v_add_co_u32_e32 v20, vcc, s0, v0
	s_mov_b32 s0, 0xb234000
	s_nop 0
	v_addc_co_u32_e32 v21, vcc, 0, v1, vcc
	v_add_co_u32_e32 v22, vcc, s0, v0
	s_mov_b32 s0, 0xb235000
	s_nop 0
	v_addc_co_u32_e32 v23, vcc, 0, v1, vcc
	v_add_co_u32_e32 v24, vcc, s0, v0
	s_mov_b32 s0, 0xb236000
	s_nop 0
	v_addc_co_u32_e32 v25, vcc, 0, v1, vcc
	s_waitcnt vmcnt(0)
	v_lshl_or_b32 v6, v6, 16, v5
	v_lshl_or_b32 v7, v8, 16, v7
	v_lshl_or_b32 v8, v26, 16, v9
	v_lshl_or_b32 v9, v28, 16, v27
	global_store_dwordx4 v[2:3], v[6:9], off offset:64
	global_load_ushort v5, v[10:11], off offset:1792
	s_nop 0
	global_load_ushort v6, v[12:13], off offset:2304
	global_load_ushort v7, v[14:15], off offset:2816
	global_load_ushort v8, v[16:17], off offset:3328
	global_load_ushort v9, v[18:19], off offset:3840
	global_load_ushort v26, v[20:21], off offset:256
	global_load_ushort v27, v[22:23], off offset:768
	global_load_ushort v28, v[24:25], off offset:1280
	v_add_co_u32_e32 v10, vcc, s0, v0
	s_mov_b32 s0, 0xb237000
	s_nop 0
	v_addc_co_u32_e32 v11, vcc, 0, v1, vcc
	v_add_co_u32_e32 v12, vcc, s0, v0
	s_mov_b32 s0, 0xb238000
	s_nop 0
	v_addc_co_u32_e32 v13, vcc, 0, v1, vcc
	v_add_co_u32_e32 v14, vcc, s0, v0
	s_mov_b32 s0, 0xb239000
	s_nop 0
	v_addc_co_u32_e32 v15, vcc, 0, v1, vcc
	v_add_co_u32_e32 v16, vcc, s0, v0
	s_mov_b32 s0, 0xb23a000
	s_nop 0
	v_addc_co_u32_e32 v17, vcc, 0, v1, vcc
	v_add_co_u32_e32 v18, vcc, s0, v0
	s_mov_b32 s0, 0xb23c000
	s_nop 0
	v_addc_co_u32_e32 v19, vcc, 0, v1, vcc
	v_add_co_u32_e32 v20, vcc, s0, v0
	s_mov_b32 s0, 0xb23d000
	s_nop 0
	v_addc_co_u32_e32 v21, vcc, 0, v1, vcc
	v_add_co_u32_e32 v22, vcc, s0, v0
	s_mov_b32 s0, 0xb23e000
	s_nop 0
	v_addc_co_u32_e32 v23, vcc, 0, v1, vcc
	v_add_co_u32_e32 v24, vcc, s0, v0
	s_mov_b32 s0, 0xb23f000
	s_nop 0
	v_addc_co_u32_e32 v25, vcc, 0, v1, vcc
	s_waitcnt vmcnt(0)
	v_lshl_or_b32 v6, v6, 16, v5
	v_lshl_or_b32 v7, v8, 16, v7
	v_lshl_or_b32 v8, v26, 16, v9
	v_lshl_or_b32 v9, v28, 16, v27
	global_store_dwordx4 v[2:3], v[6:9], off offset:80
	global_load_ushort v5, v[10:11], off offset:1792
	s_nop 0
	global_load_ushort v6, v[12:13], off offset:2304
	global_load_ushort v7, v[14:15], off offset:2816
	global_load_ushort v8, v[16:17], off offset:3328
	global_load_ushort v9, v[18:19], off offset:3840
	global_load_ushort v26, v[20:21], off offset:256
	global_load_ushort v27, v[22:23], off offset:768
	s_nop 0
	global_load_ushort v24, v[24:25], off offset:1280
	v_add_co_u32_e32 v10, vcc, s0, v0
	s_mov_b32 s0, 0xb240000
	s_nop 0
	v_addc_co_u32_e32 v11, vcc, 0, v1, vcc
	v_add_co_u32_e32 v12, vcc, s0, v0
	s_mov_b32 s0, 0xb241000
	s_nop 0
	v_addc_co_u32_e32 v13, vcc, 0, v1, vcc
	v_add_co_u32_e32 v14, vcc, s0, v0
	s_mov_b32 s0, 0xb242000
	s_nop 0
	v_addc_co_u32_e32 v15, vcc, 0, v1, vcc
	v_add_co_u32_e32 v16, vcc, s0, v0
	s_mov_b32 s0, 0xb243000
	s_nop 0
	v_addc_co_u32_e32 v17, vcc, 0, v1, vcc
	v_add_co_u32_e32 v18, vcc, s0, v0
	s_mov_b32 s0, 0xb245000
	s_nop 0
	v_addc_co_u32_e32 v19, vcc, 0, v1, vcc
	v_add_co_u32_e32 v20, vcc, s0, v0
	s_mov_b32 s0, 0xb246000
	s_nop 0
	v_addc_co_u32_e32 v21, vcc, 0, v1, vcc
	v_add_co_u32_e32 v22, vcc, s0, v0
	s_mov_b32 s0, 0xb247000
	s_nop 0
	v_addc_co_u32_e32 v23, vcc, 0, v1, vcc
	v_add_co_u32_e32 v0, vcc, s0, v0
	v_readlane_b32 s0, v255, 7
	s_nop 0
	v_addc_co_u32_e32 v1, vcc, 0, v1, vcc
	v_readlane_b32 s1, v255, 8
	s_lshl_b64 s[0:1], s[0:1], 2
	s_add_u32 s0, s8, s0
	s_addc_u32 s1, s9, s1
	s_waitcnt vmcnt(0)
	v_lshl_or_b32 v6, v6, 16, v5
	v_lshl_or_b32 v7, v8, 16, v7
	v_lshl_or_b32 v8, v26, 16, v9
	v_lshl_or_b32 v9, v24, 16, v27
	global_store_dwordx4 v[2:3], v[6:9], off offset:96
	global_load_ushort v5, v[10:11], off offset:1792
	s_nop 0
	global_load_ushort v6, v[12:13], off offset:2304
	global_load_ushort v7, v[14:15], off offset:2816
	global_load_ushort v10, v[16:17], off offset:3328
	global_load_ushort v11, v[18:19], off offset:3840
	s_nop 0
	global_load_ushort v12, v[20:21], off offset:256
	global_load_ushort v13, v[22:23], off offset:768
	global_load_ushort v14, v[0:1], off offset:1280
	v_mov_b32_e32 v0, 0x200
	v_lshl_add_u32 v54, v4, 3, v0
	v_mov_b32_e32 v15, v236
	v_mov_b64_e32 v[0:1], s[10:11]
	v_mad_u64_u32 v[8:9], s[4:5], v54, s6, v[0:1]
	s_waitcnt vmcnt(0)
	v_lshl_or_b32 v4, v6, 16, v5
	v_lshl_or_b32 v5, v10, 16, v7
	v_lshl_or_b32 v6, v12, 16, v11
	v_lshl_or_b32 v7, v14, 16, v13
	global_store_dwordx4 v[2:3], v[4:7], off offset:112
	s_nop 0
	v_and_b32_e32 v14, 15, v15
	v_bfe_u32 v17, v15, 4, 2
	v_lshlrev_b32_e32 v19, 2, v14
	v_lshlrev_b32_e32 v2, 6, v17
	v_or_b32_e32 v21, 8, v17
	v_lshlrev_b32_e32 v160, 4, v14
	v_or_b32_e32 v23, 0x100, v19
	v_min_u32_e32 v3, 9, v21
	v_or_b32_e32 v20, v2, v19
	v_lshl_add_u64 v[0:1], s[0:1], 0, v[160:161]
	v_or_b32_e32 v16, v2, v23
	v_lshlrev_b32_e32 v24, 6, v3
	s_mov_b64 s[0:1], 0x2000
	v_lshlrev_b32_e32 v160, 1, v20
	v_lshl_add_u64 v[4:5], v[0:1], 0, s[0:1]
	v_add_co_u32_e32 v0, vcc, s20, v0
	v_lshl_add_u64 v[10:11], v[8:9], 0, v[160:161]
	v_lshlrev_b32_e32 v160, 1, v16
	v_or_b32_e32 v22, v24, v19
	v_addc_co_u32_e32 v1, vcc, 0, v1, vcc
	v_lshl_add_u64 v[12:13], v[8:9], 0, v[160:161]
	v_lshlrev_b32_e32 v160, 1, v22
	global_load_dwordx4 v[0:3], v[0:1], off
	s_nop 0
	global_load_dwordx4 v[4:7], v[4:5], off offset:1024
	v_lshl_add_u64 v[8:9], v[8:9], 0, v[160:161]
	global_load_dwordx2 v[42:43], v[10:11], off offset:512
	global_load_dwordx2 v[40:41], v[12:13], off offset:512
	global_load_dwordx2 v[34:35], v[8:9], off offset:512
	v_and_b32_e32 v8, 63, v15
	v_and_b32_e32 v9, 4, v15
	v_lshlrev_b32_e32 v160, 3, v8
	v_cmp_eq_u32_e64 s[36:37], 0, v9
	v_cmp_gt_u32_e64 s[38:39], 8, v14
	v_and_b32_e32 v14, 12, v19
	v_lshl_add_u64 v[8:9], s[8:9], 0, v[160:161]
	s_mov_b64 s[0:1], 0x16f00000
	v_lshl_add_u64 v[12:13], v[8:9], 0, s[0:1]
	v_cvt_f32_ubyte0_e32 v8, v14
	v_mul_f32_e32 v8, 0xbf549a78, v8
	v_exp_f32_e32 v56, v8
	v_or_b32_e32 v8, 1, v14
	v_cvt_f32_ubyte0_e32 v8, v8
	v_mul_f32_e32 v8, 0xbf549a78, v8
	v_exp_f32_e32 v57, v8
	v_or_b32_e32 v8, 2, v14
	v_cvt_f32_ubyte0_e32 v8, v8
	v_mul_f32_e32 v8, 0xbf549a78, v8
	v_exp_f32_e32 v58, v8
	v_or_b32_e32 v8, 3, v14
	v_cvt_f32_ubyte0_e32 v8, v8
	v_mul_f32_e32 v8, 0xbf549a78, v8
	v_exp_f32_e32 v59, v8
	v_mad_i64_i32 v[8:9], s[0:1], v54, s6, 0
	v_add_u32_e32 v18, 0x100, v16
	v_or_b32_e32 v24, v24, v23
	v_or_b32_e32 v8, v8, v160
	v_cmp_gt_u32_e32 vcc, 10, v21
	v_lshlrev_b32_e64 v55, v17, 1
	v_lshl_add_u64 v[10:11], s[10:11], 0, v[160:161]
	v_lshl_add_u64 v[14:15], s[10:11], 0, v[8:9]
	v_lshlrev_b32_e32 v8, 1, v16
	v_lshlrev_b32_e32 v16, 1, v18
	v_lshlrev_b32_e32 v18, 1, v24
	v_lshlrev_b32_e32 v20, 1, v20
	v_lshlrev_b32_e32 v22, 1, v22
	v_mov_b32_e32 v21, 0
	s_branch .LBB0_508
